# attention row-max cross-lane reduce via permlane16/32 swap instead of ds_swizzle+ds_bpermute
# speedup vs baseline: 1.0218x; 1.0218x over previous
; DI float max3_(float a, float b, float c) { float r; asm("v_max3_f32 %0, %1, %2, %3" : "=v"(r) : "v"(a), "v"(b), "v"(c)); return r; }
; template <int DQK, bool BIAS>
; __device__ __forceinline__ void attn_pass(const hf* __restrict__ Q, int ldq, const hf* __restrict__ Kp, int ldk, const hf* __restrict__ VT,
;                                           int s0, int L, int q0, float scale_l2, const float* sBias, f4 (&oacc)[8][4], char* smem) {
;     ...
;       float mx = -1e30f;
; #pragma unroll
;       for (int mk = 0; mk < 4; ++mk) { mx = max3_(mx, sacc[mk][nq][0], sacc[mk][nq][1]); mx = max3_(mx, sacc[mk][nq][2], sacc[mk][nq][3]); }
;       mx = max3_(mx, shx(mx, 16), mx); mx = max3_(mx, shx(mx, 32), mx);
;       if (!BIAS) mx *= scale_l2;
;       const bool upd = mx > mrun[nq] + 8.f;
;       const float mnew = upd ? mx : mrun[nq];
;       if (__builtin_amdgcn_ballot_w64(upd) != 0) {
;         const float alpha = __builtin_amdgcn_exp2f(mrun[nq] - mnew);
;         lrun[nq] *= alpha;
; #pragma unroll
;         for (int md = 0; md < 8; ++md) { oacc[md][nq][0] *= alpha; oacc[md][nq][1] *= alpha; oacc[md][nq][2] *= alpha; oacc[md][nq][3] *= alpha; }
;       }
.LBB0_1956:
	v_max3_f32 v176, v199, v32, v33
	s_nop 0
	v_max3_f32 v176, v176, v34, v35
	s_nop 0
	v_max3_f32 v176, v176, v44, v45
	s_nop 0
	v_max3_f32 v176, v176, v46, v47
	s_nop 0
	v_max3_f32 v176, v176, v40, v41
	s_nop 0
	v_max3_f32 v176, v176, v42, v43
	s_nop 0
	v_max3_f32 v176, v176, v36, v37
	s_nop 0
	v_max3_f32 v176, v176, v38, v39
	v_mov_b32_e32 v177, v176
	s_nop 1
	v_permlane16_swap_b32_e32 v177, v176
	v_max_f32_e32 v176, v176, v177
	v_mov_b32_e32 v177, v176
	s_nop 1
	v_permlane32_swap_b32_e32 v177, v176
	v_max_f32_e32 v176, v176, v177
	v_add_f32_e32 v177, 0x41000000, v198
	v_cmp_gt_f32_e32 vcc, v176, v177
	s_nop 1
	v_cndmask_b32_e32 v176, v198, v176, vcc
	s_cbranch_vccz .LBB0_1958
	v_sub_f32_e32 v177, v198, v176
	v_exp_f32_e32 v178, v177
	s_nop 0
	v_pk_mul_f32 v[172:173], v[172:173], v[178:179] op_sel_hi:[1,0]
	v_pk_mul_f32 v[164:165], v[164:165], v[178:179] op_sel_hi:[1,0]
	v_pk_mul_f32 v[168:169], v[168:169], v[178:179] op_sel_hi:[1,0]
	v_pk_mul_f32 v[160:161], v[160:161], v[178:179] op_sel_hi:[1,0]
	v_pk_mul_f32 v[92:93], v[92:93], v[178:179] op_sel_hi:[1,0]
	v_pk_mul_f32 v[88:89], v[88:89], v[178:179] op_sel_hi:[1,0]
	v_pk_mul_f32 v[86:87], v[86:87], v[178:179] op_sel_hi:[1,0]
	v_pk_mul_f32 v[82:83], v[82:83], v[178:179] op_sel_hi:[1,0]
	v_pk_mul_f32 v[174:175], v[174:175], v[178:179] op_sel_hi:[1,0]
	v_pk_mul_f32 v[166:167], v[166:167], v[178:179] op_sel_hi:[1,0]
	v_pk_mul_f32 v[170:171], v[170:171], v[178:179] op_sel_hi:[1,0]
	v_pk_mul_f32 v[162:163], v[162:163], v[178:179] op_sel_hi:[1,0]
	v_pk_mul_f32 v[94:95], v[94:95], v[178:179] op_sel_hi:[1,0]
	v_pk_mul_f32 v[90:91], v[90:91], v[178:179] op_sel_hi:[1,0]
	v_pk_mul_f32 v[84:85], v[84:85], v[178:179] op_sel_hi:[1,0]
	v_pk_mul_f32 v[80:81], v[80:81], v[178:179] op_sel_hi:[1,0]
	v_accvgpr_write_b32 a95, v87
	v_accvgpr_write_b32 a107, v83
	v_accvgpr_write_b32 a76, v88
	v_accvgpr_write_b32 a64, v92
	v_accvgpr_write_b32 a44, v160
	v_accvgpr_write_b32 a24, v168
	v_accvgpr_write_b32 a8, v164
	v_accvgpr_write_b32 a0, v172
	v_mul_f32_e32 v245, v245, v178
	v_accvgpr_write_b32 a106, v82
	v_accvgpr_write_b32 a105, v81
	v_accvgpr_write_b32 a104, v80
	v_accvgpr_write_b32 a94, v86
	v_accvgpr_write_b32 a93, v85
	v_accvgpr_write_b32 a92, v84
	v_accvgpr_write_b32 a77, v89
	v_accvgpr_write_b32 a78, v90
	v_accvgpr_write_b32 a79, v91
	v_accvgpr_write_b32 a65, v93
	v_accvgpr_write_b32 a66, v94
	v_accvgpr_write_b32 a67, v95
	v_accvgpr_write_b32 a45, v161
	v_accvgpr_write_b32 a46, v162
	v_accvgpr_write_b32 a47, v163
	v_accvgpr_write_b32 a25, v169
	v_accvgpr_write_b32 a26, v170
	v_accvgpr_write_b32 a27, v171
	v_accvgpr_write_b32 a9, v165
	v_accvgpr_write_b32 a10, v166
	v_accvgpr_write_b32 a11, v167
	v_accvgpr_write_b32 a1, v173
	v_accvgpr_write_b32 a2, v174
	v_accvgpr_write_b32 a3, v175

; DI float max3_(float a, float b, float c) { float r; asm("v_max3_f32 %0, %1, %2, %3" : "=v"(r) : "v"(a), "v"(b), "v"(c)); return r; }
; template <int DQK, bool BIAS>
; __device__ __forceinline__ void attn_pass(const hf* __restrict__ Q, int ldq, const hf* __restrict__ Kp, int ldk, const hf* __restrict__ VT,
;                                           int s0, int L, int q0, float scale_l2, const float* sBias, f4 (&oacc)[8][4], char* smem) {
;     ...
;       float mx = -1e30f;
; #pragma unroll
;       for (int mk = 0; mk < 4; ++mk) { mx = max3_(mx, sacc[mk][nq][0], sacc[mk][nq][1]); mx = max3_(mx, sacc[mk][nq][2], sacc[mk][nq][3]); }
;       mx = max3_(mx, shx(mx, 16), mx); mx = max3_(mx, shx(mx, 32), mx);
;       if (!BIAS) mx *= scale_l2;
;       const bool upd = mx > mrun[nq] + 8.f;
;       const float mnew = upd ? mx : mrun[nq];
;       if (__builtin_amdgcn_ballot_w64(upd) != 0) {
;         const float alpha = __builtin_amdgcn_exp2f(mrun[nq] - mnew);
;         lrun[nq] *= alpha;
; #pragma unroll
;         for (int md = 0; md < 8; ++md) { oacc[md][nq][0] *= alpha; oacc[md][nq][1] *= alpha; oacc[md][nq][2] *= alpha; oacc[md][nq][3] *= alpha; }
;       }
.LBB0_1962:
	v_max3_f32 v160, v199, v80, v81
	s_nop 0
	v_max3_f32 v160, v160, v82, v83
	s_nop 0
	v_max3_f32 v160, v160, v92, v93
	s_nop 0
	v_max3_f32 v160, v160, v94, v95
	s_nop 0
	v_max3_f32 v160, v160, v84, v85
	s_nop 0
	v_max3_f32 v160, v160, v86, v87
	s_nop 0
	v_max3_f32 v160, v160, v88, v89
	s_nop 0
	v_max3_f32 v160, v160, v90, v91
	v_mov_b32_e32 v161, v160
	s_nop 1
	v_permlane16_swap_b32_e32 v161, v160
	v_max_f32_e32 v160, v160, v161
	v_mov_b32_e32 v161, v160
	s_nop 1
	v_permlane32_swap_b32_e32 v161, v160
	v_max_f32_e32 v160, v160, v161
	v_add_f32_e32 v161, 0x41000000, v253
	v_cmp_gt_f32_e32 vcc, v160, v161
	s_nop 1
	v_cndmask_b32_e32 v160, v253, v160, vcc
	s_cbranch_vccz .LBB0_1964
	v_sub_f32_e32 v161, v253, v160
	v_exp_f32_e32 v162, v161
	s_nop 0
	v_pk_mul_f32 v[156:157], v[156:157], v[162:163] op_sel_hi:[1,0]
	v_pk_mul_f32 v[148:149], v[148:149], v[162:163] op_sel_hi:[1,0]
	v_pk_mul_f32 v[152:153], v[152:153], v[162:163] op_sel_hi:[1,0]
	v_pk_mul_f32 v[144:145], v[144:145], v[162:163] op_sel_hi:[1,0]
	v_pk_mul_f32 v[140:141], v[140:141], v[162:163] op_sel_hi:[1,0]
	v_pk_mul_f32 v[136:137], v[136:137], v[162:163] op_sel_hi:[1,0]
	v_pk_mul_f32 v[132:133], v[132:133], v[162:163] op_sel_hi:[1,0]
	v_pk_mul_f32 v[128:129], v[128:129], v[162:163] op_sel_hi:[1,0]
	v_pk_mul_f32 v[158:159], v[158:159], v[162:163] op_sel_hi:[1,0]
	v_pk_mul_f32 v[150:151], v[150:151], v[162:163] op_sel_hi:[1,0]
	v_pk_mul_f32 v[154:155], v[154:155], v[162:163] op_sel_hi:[1,0]
	v_pk_mul_f32 v[146:147], v[146:147], v[162:163] op_sel_hi:[1,0]
	v_pk_mul_f32 v[142:143], v[142:143], v[162:163] op_sel_hi:[1,0]
	v_pk_mul_f32 v[138:139], v[138:139], v[162:163] op_sel_hi:[1,0]
	v_pk_mul_f32 v[134:135], v[134:135], v[162:163] op_sel_hi:[1,0]
	v_pk_mul_f32 v[130:131], v[130:131], v[162:163] op_sel_hi:[1,0]
	v_accvgpr_write_b32 a100, v132
	v_accvgpr_write_b32 a116, v128
	v_accvgpr_write_b32 a84, v136
	v_accvgpr_write_b32 a68, v140
	v_accvgpr_write_b32 a52, v144
	v_accvgpr_write_b32 a36, v152
	v_accvgpr_write_b32 a16, v148
	v_accvgpr_write_b32 a4, v156
	v_mul_f32_e32 v243, v243, v162
	v_accvgpr_write_b32 a117, v129
	v_accvgpr_write_b32 a118, v130
	v_accvgpr_write_b32 a119, v131
	v_accvgpr_write_b32 a101, v133
	v_accvgpr_write_b32 a102, v134
	v_accvgpr_write_b32 a103, v135
	v_accvgpr_write_b32 a85, v137
	v_accvgpr_write_b32 a86, v138
	v_accvgpr_write_b32 a87, v139
	v_accvgpr_write_b32 a69, v141
	v_accvgpr_write_b32 a70, v142
	v_accvgpr_write_b32 a71, v143
	v_accvgpr_write_b32 a53, v145
	v_accvgpr_write_b32 a54, v146
	v_accvgpr_write_b32 a55, v147
	v_accvgpr_write_b32 a37, v153
	v_accvgpr_write_b32 a38, v154
	v_accvgpr_write_b32 a39, v155
	v_accvgpr_write_b32 a17, v149
	v_accvgpr_write_b32 a18, v150
	v_accvgpr_write_b32 a19, v151
	v_accvgpr_write_b32 a5, v157
	v_accvgpr_write_b32 a6, v158
	v_accvgpr_write_b32 a7, v159

; DI float max3_(float a, float b, float c) { float r; asm("v_max3_f32 %0, %1, %2, %3" : "=v"(r) : "v"(a), "v"(b), "v"(c)); return r; }
; template <int DQK, bool BIAS>
; __device__ __forceinline__ void attn_pass(const hf* __restrict__ Q, int ldq, const hf* __restrict__ Kp, int ldk, const hf* __restrict__ VT,
;                                           int s0, int L, int q0, float scale_l2, const float* sBias, f4 (&oacc)[8][4], char* smem) {
;     ...
;       float mx = -1e30f;
; #pragma unroll
;       for (int mk = 0; mk < 4; ++mk) { mx = max3_(mx, sacc[mk][nq][0], sacc[mk][nq][1]); mx = max3_(mx, sacc[mk][nq][2], sacc[mk][nq][3]); }
;       mx = max3_(mx, shx(mx, 16), mx); mx = max3_(mx, shx(mx, 32), mx);
;       if (!BIAS) mx *= scale_l2;
;       const bool upd = mx > mrun[nq] + 8.f;
;       const float mnew = upd ? mx : mrun[nq];
;       if (__builtin_amdgcn_ballot_w64(upd) != 0) {
;         const float alpha = __builtin_amdgcn_exp2f(mrun[nq] - mnew);
;         lrun[nq] *= alpha;
; #pragma unroll
;         for (int md = 0; md < 8; ++md) { oacc[md][nq][0] *= alpha; oacc[md][nq][1] *= alpha; oacc[md][nq][2] *= alpha; oacc[md][nq][3] *= alpha; }
;       }
.LBB0_1968:
	v_max3_f32 v144, v199, v128, v129
	s_nop 0
	v_max3_f32 v144, v144, v130, v131
	s_nop 0
	v_max3_f32 v144, v144, v140, v141
	s_nop 0
	v_max3_f32 v144, v144, v142, v143
	s_nop 0
	v_max3_f32 v144, v144, v136, v137
	s_nop 0
	v_max3_f32 v144, v144, v138, v139
	s_nop 0
	v_max3_f32 v144, v144, v132, v133
	s_nop 0
	v_max3_f32 v144, v144, v134, v135
	v_mov_b32_e32 v145, v144
	s_nop 1
	v_permlane16_swap_b32_e32 v145, v144
	v_max_f32_e32 v144, v144, v145
	v_mov_b32_e32 v145, v144
	s_nop 1
	v_permlane32_swap_b32_e32 v145, v144
	v_max_f32_e32 v144, v144, v145
	v_add_f32_e32 v145, 0x41000000, v247
	v_cmp_gt_f32_e32 vcc, v144, v145
	s_nop 1
	v_cndmask_b32_e32 v144, v247, v144, vcc
	s_cbranch_vccz .LBB0_1970
	v_sub_f32_e32 v145, v247, v144
	v_exp_f32_e32 v146, v145
	s_nop 0
	v_pk_mul_f32 v[124:125], v[124:125], v[146:147] op_sel_hi:[1,0]
	v_pk_mul_f32 v[116:117], v[116:117], v[146:147] op_sel_hi:[1,0]
	v_pk_mul_f32 v[120:121], v[120:121], v[146:147] op_sel_hi:[1,0]
	v_pk_mul_f32 v[112:113], v[112:113], v[146:147] op_sel_hi:[1,0]
	v_pk_mul_f32 v[108:109], v[108:109], v[146:147] op_sel_hi:[1,0]
	v_pk_mul_f32 v[104:105], v[104:105], v[146:147] op_sel_hi:[1,0]
	v_pk_mul_f32 v[102:103], v[102:103], v[146:147] op_sel_hi:[1,0]
	v_pk_mul_f32 v[98:99], v[98:99], v[146:147] op_sel_hi:[1,0]
	v_pk_mul_f32 v[126:127], v[126:127], v[146:147] op_sel_hi:[1,0]
	v_pk_mul_f32 v[118:119], v[118:119], v[146:147] op_sel_hi:[1,0]
	v_pk_mul_f32 v[122:123], v[122:123], v[146:147] op_sel_hi:[1,0]
	v_pk_mul_f32 v[114:115], v[114:115], v[146:147] op_sel_hi:[1,0]
	v_pk_mul_f32 v[110:111], v[110:111], v[146:147] op_sel_hi:[1,0]
	v_pk_mul_f32 v[106:107], v[106:107], v[146:147] op_sel_hi:[1,0]
	v_pk_mul_f32 v[100:101], v[100:101], v[146:147] op_sel_hi:[1,0]
	v_pk_mul_f32 v[96:97], v[96:97], v[146:147] op_sel_hi:[1,0]
	v_accvgpr_write_b32 a111, v103
	v_accvgpr_write_b32 a123, v99
	v_accvgpr_write_b32 a88, v104
	v_accvgpr_write_b32 a72, v108
	v_accvgpr_write_b32 a56, v112
	v_accvgpr_write_b32 a40, v120
	v_accvgpr_write_b32 a28, v116
	v_accvgpr_write_b32 a12, v124
	v_mul_f32_e32 v242, v242, v146
	v_accvgpr_write_b32 a122, v98
	v_accvgpr_write_b32 a121, v97
	v_accvgpr_write_b32 a120, v96
	v_accvgpr_write_b32 a110, v102
	v_accvgpr_write_b32 a109, v101
	v_accvgpr_write_b32 a108, v100
	v_accvgpr_write_b32 a89, v105
	v_accvgpr_write_b32 a90, v106
	v_accvgpr_write_b32 a91, v107
	v_accvgpr_write_b32 a73, v109
	v_accvgpr_write_b32 a74, v110
	v_accvgpr_write_b32 a75, v111
	v_accvgpr_write_b32 a57, v113
	v_accvgpr_write_b32 a58, v114
	v_accvgpr_write_b32 a59, v115
	v_accvgpr_write_b32 a41, v121
	v_accvgpr_write_b32 a42, v122
	v_accvgpr_write_b32 a43, v123
	v_accvgpr_write_b32 a29, v117
	v_accvgpr_write_b32 a30, v118
	v_accvgpr_write_b32 a31, v119
	v_accvgpr_write_b32 a13, v125
	v_accvgpr_write_b32 a14, v126
	v_accvgpr_write_b32 a15, v127

; DI float max3_(float a, float b, float c) { float r; asm("v_max3_f32 %0, %1, %2, %3" : "=v"(r) : "v"(a), "v"(b), "v"(c)); return r; }
; template <int DQK, bool BIAS>
; __device__ __forceinline__ void attn_pass(const hf* __restrict__ Q, int ldq, const hf* __restrict__ Kp, int ldk, const hf* __restrict__ VT,
;                                           int s0, int L, int q0, float scale_l2, const float* sBias, f4 (&oacc)[8][4], char* smem) {
;     ...
;       float mx = -1e30f;
; #pragma unroll
;       for (int mk = 0; mk < 4; ++mk) { mx = max3_(mx, sacc[mk][nq][0], sacc[mk][nq][1]); mx = max3_(mx, sacc[mk][nq][2], sacc[mk][nq][3]); }
;       mx = max3_(mx, shx(mx, 16), mx); mx = max3_(mx, shx(mx, 32), mx);
;       if (!BIAS) mx *= scale_l2;
;       const bool upd = mx > mrun[nq] + 8.f;
;       const float mnew = upd ? mx : mrun[nq];
;       if (__builtin_amdgcn_ballot_w64(upd) != 0) {
;         const float alpha = __builtin_amdgcn_exp2f(mrun[nq] - mnew);
;         lrun[nq] *= alpha;
; #pragma unroll
;         for (int md = 0; md < 8; ++md) { oacc[md][nq][0] *= alpha; oacc[md][nq][1] *= alpha; oacc[md][nq][2] *= alpha; oacc[md][nq][3] *= alpha; }
;       }
.LBB0_1974:
	v_max3_f32 v112, v199, v96, v97
	s_nop 0
	v_max3_f32 v112, v112, v98, v99
	s_nop 0
	v_max3_f32 v112, v112, v104, v105
	s_nop 0
	v_max3_f32 v112, v112, v106, v107
	s_nop 0
	v_max3_f32 v112, v112, v100, v101
	s_nop 0
	v_max3_f32 v112, v112, v102, v103
	s_nop 0
	v_max3_f32 v112, v112, v108, v109
	s_nop 0
	v_max3_f32 v112, v112, v110, v111
	v_mov_b32_e32 v113, v112
	s_nop 1
	v_permlane16_swap_b32_e32 v113, v112
	v_max_f32_e32 v112, v112, v113
	v_mov_b32_e32 v113, v112
	s_nop 1
	v_permlane32_swap_b32_e32 v113, v112
	v_max_f32_e32 v112, v112, v113
	v_add_f32_e32 v113, 0x41000000, v246
	v_cmp_gt_f32_e32 vcc, v112, v113
	s_nop 1
	v_cndmask_b32_e32 v112, v246, v112, vcc
	s_cbranch_vccz .LBB0_1976
	v_sub_f32_e32 v113, v246, v112
	v_exp_f32_e32 v114, v113
	s_nop 0
	v_pk_mul_f32 v[76:77], v[76:77], v[114:115] op_sel_hi:[1,0]
	v_pk_mul_f32 v[68:69], v[68:69], v[114:115] op_sel_hi:[1,0]
	v_pk_mul_f32 v[72:73], v[72:73], v[114:115] op_sel_hi:[1,0]
	v_pk_mul_f32 v[64:65], v[64:65], v[114:115] op_sel_hi:[1,0]
	v_pk_mul_f32 v[62:63], v[62:63], v[114:115] op_sel_hi:[1,0]
	v_pk_mul_f32 v[58:59], v[58:59], v[114:115] op_sel_hi:[1,0]
	v_pk_mul_f32 v[54:55], v[54:55], v[114:115] op_sel_hi:[1,0]
	v_pk_mul_f32 v[50:51], v[50:51], v[114:115] op_sel_hi:[1,0]
	v_pk_mul_f32 v[78:79], v[78:79], v[114:115] op_sel_hi:[1,0]
	v_pk_mul_f32 v[70:71], v[70:71], v[114:115] op_sel_hi:[1,0]
	v_pk_mul_f32 v[74:75], v[74:75], v[114:115] op_sel_hi:[1,0]
	v_pk_mul_f32 v[66:67], v[66:67], v[114:115] op_sel_hi:[1,0]
	v_pk_mul_f32 v[60:61], v[60:61], v[114:115] op_sel_hi:[1,0]
	v_pk_mul_f32 v[56:57], v[56:57], v[114:115] op_sel_hi:[1,0]
	v_pk_mul_f32 v[52:53], v[52:53], v[114:115] op_sel_hi:[1,0]
	v_pk_mul_f32 v[48:49], v[48:49], v[114:115] op_sel_hi:[1,0]
	v_accvgpr_write_b32 a115, v55
	v_accvgpr_write_b32 a127, v51
	v_accvgpr_write_b32 a99, v59
	v_accvgpr_write_b32 a83, v63
	v_accvgpr_write_b32 a60, v64
	v_accvgpr_write_b32 a48, v72
	v_accvgpr_write_b32 a32, v68
	v_accvgpr_write_b32 a20, v76
	v_mul_f32_e32 v233, v233, v114
	v_accvgpr_write_b32 a126, v50
	v_accvgpr_write_b32 a125, v49
	v_accvgpr_write_b32 a124, v48
	v_accvgpr_write_b32 a114, v54
	v_accvgpr_write_b32 a113, v53
	v_accvgpr_write_b32 a112, v52
	v_accvgpr_write_b32 a98, v58
	v_accvgpr_write_b32 a97, v57
	v_accvgpr_write_b32 a96, v56
	v_accvgpr_write_b32 a82, v62
	v_accvgpr_write_b32 a81, v61
	v_accvgpr_write_b32 a80, v60
	v_accvgpr_write_b32 a61, v65
	v_accvgpr_write_b32 a62, v66
	v_accvgpr_write_b32 a63, v67
	v_accvgpr_write_b32 a49, v73
	v_accvgpr_write_b32 a50, v74
	v_accvgpr_write_b32 a51, v75
	v_accvgpr_write_b32 a33, v69
	v_accvgpr_write_b32 a34, v70
	v_accvgpr_write_b32 a35, v71
	v_accvgpr_write_b32 a21, v77
	v_accvgpr_write_b32 a22, v78
	v_accvgpr_write_b32 a23, v79

; DI float max3_(float a, float b, float c) { float r; asm("v_max3_f32 %0, %1, %2, %3" : "=v"(r) : "v"(a), "v"(b), "v"(c)); return r; }
; template <int DQK, bool BIAS>
; __device__ __forceinline__ void attn_pass(const hf* __restrict__ Q, int ldq, const hf* __restrict__ Kp, int ldk, const hf* __restrict__ VT,
;                                           int s0, int L, int q0, float scale_l2, const float* sBias, f4 (&oacc)[8][4], char* smem) {
;     ...
;       float mx = -1e30f;
; #pragma unroll
;       for (int mk = 0; mk < 4; ++mk) { mx = max3_(mx, sacc[mk][nq][0], sacc[mk][nq][1]); mx = max3_(mx, sacc[mk][nq][2], sacc[mk][nq][3]); }
;       mx = max3_(mx, shx(mx, 16), mx); mx = max3_(mx, shx(mx, 32), mx);
;       if (!BIAS) mx *= scale_l2;
;       const bool upd = mx > mrun[nq] + 8.f;
;       const float mnew = upd ? mx : mrun[nq];
;       if (__builtin_amdgcn_ballot_w64(upd) != 0) {
;         const float alpha = __builtin_amdgcn_exp2f(mrun[nq] - mnew);
;         lrun[nq] *= alpha;
; #pragma unroll
;         for (int md = 0; md < 8; ++md) { oacc[md][nq][0] *= alpha; oacc[md][nq][1] *= alpha; oacc[md][nq][2] *= alpha; oacc[md][nq][3] *= alpha; }
;       }
.LBB0_1998:
	v_accvgpr_read_b32 v68, a168
	v_accvgpr_read_b32 v69, a169
	v_max3_f32 v48, v226, v68, v69
	v_accvgpr_read_b32 v70, a170
	v_accvgpr_read_b32 v71, a171
	v_accvgpr_read_b32 v64, a176
	v_max3_f32 v48, v48, v70, v71
	v_accvgpr_read_b32 v65, a177
	v_max3_f32 v48, v48, v64, v65
	v_accvgpr_read_b32 v66, a178
	v_accvgpr_read_b32 v67, a179
	v_accvgpr_read_b32 v60, a184
	v_max3_f32 v48, v48, v66, v67
	v_accvgpr_read_b32 v61, a185
	v_max3_f32 v48, v48, v60, v61
	v_accvgpr_read_b32 v62, a186
	v_accvgpr_read_b32 v63, a187
	v_accvgpr_read_b32 v56, a188
	v_max3_f32 v48, v48, v62, v63
	v_accvgpr_read_b32 v57, a189
	v_max3_f32 v48, v48, v56, v57
	v_accvgpr_read_b32 v58, a190
	v_accvgpr_read_b32 v59, a191
	v_max3_f32 v48, v48, v58, v59
	v_mov_b32_e32 v50, v224
	v_mov_b32_e32 v49, v48
	v_mov_b32_e32 v210, v48
	s_nop 1
	v_permlane16_swap_b32_e32 v49, v210
	v_max_f32_e32 v210, v49, v210
	v_mov_b32_e32 v211, v210
	v_mov_b32_e32 v49, v210
	s_nop 1
	v_permlane32_swap_b32_e32 v211, v49
	v_max_f32_e32 v210, v211, v49
	v_accvgpr_read_b32 v80, a160
	v_add_f32_e32 v211, 0x41000000, v225
	v_mul_f32_e32 v210, 0x3e16c740, v210
	v_accvgpr_read_b32 v72, a164
	v_accvgpr_read_b32 v52, a172
	v_accvgpr_read_b32 v48, a180
	v_cmp_gt_f32_e32 vcc, v210, v211
	v_accvgpr_read_b32 v81, a161
	v_accvgpr_read_b32 v82, a162
	v_accvgpr_read_b32 v83, a163
	v_accvgpr_read_b32 v73, a165
	v_accvgpr_read_b32 v74, a166
	v_accvgpr_read_b32 v75, a167
	v_accvgpr_read_b32 v53, a173
	v_accvgpr_read_b32 v54, a174
	v_accvgpr_read_b32 v55, a175
	v_accvgpr_read_b32 v49, a181
	v_accvgpr_read_b32 v50, a182
	v_accvgpr_read_b32 v51, a183
	v_cndmask_b32_e32 v241, v225, v210, vcc
	s_cbranch_vccz .LBB0_2000
	v_sub_f32_e32 v210, v225, v241
	v_exp_f32_e32 v210, v210
	s_nop 0
	v_pk_mul_f32 v[204:205], v[204:205], v[210:211] op_sel_hi:[1,0]
	v_pk_mul_f32 v[200:201], v[200:201], v[210:211] op_sel_hi:[1,0]
	v_pk_mul_f32 v[196:197], v[196:197], v[210:211] op_sel_hi:[1,0]
	v_pk_mul_f32 v[192:193], v[192:193], v[210:211] op_sel_hi:[1,0]
	v_pk_mul_f32 v[172:173], v[172:173], v[210:211] op_sel_hi:[1,0]
	v_pk_mul_f32 v[168:169], v[168:169], v[210:211] op_sel_hi:[1,0]
	v_pk_mul_f32 v[164:165], v[164:165], v[210:211] op_sel_hi:[1,0]
	v_pk_mul_f32 v[160:161], v[160:161], v[210:211] op_sel_hi:[1,0]
	v_pk_mul_f32 v[206:207], v[206:207], v[210:211] op_sel_hi:[1,0]
	v_pk_mul_f32 v[202:203], v[202:203], v[210:211] op_sel_hi:[1,0]
	v_pk_mul_f32 v[198:199], v[198:199], v[210:211] op_sel_hi:[1,0]
	v_pk_mul_f32 v[194:195], v[194:195], v[210:211] op_sel_hi:[1,0]
	v_pk_mul_f32 v[174:175], v[174:175], v[210:211] op_sel_hi:[1,0]
	v_pk_mul_f32 v[170:171], v[170:171], v[210:211] op_sel_hi:[1,0]
	v_pk_mul_f32 v[166:167], v[166:167], v[210:211] op_sel_hi:[1,0]
	v_pk_mul_f32 v[162:163], v[162:163], v[210:211] op_sel_hi:[1,0]
	v_accvgpr_write_b32 a92, v164
	v_accvgpr_write_b32 a108, v160
	v_accvgpr_write_b32 a76, v168
	v_accvgpr_write_b32 a64, v172
	v_accvgpr_write_b32 a40, v192
	v_accvgpr_write_b32 a28, v196
	v_accvgpr_write_b32 a8, v200
	v_accvgpr_write_b32 a0, v204
	v_mul_f32_e32 v240, v240, v210
	v_accvgpr_write_b32 a109, v161
	v_accvgpr_write_b32 a110, v162
	v_accvgpr_write_b32 a111, v163
	v_accvgpr_write_b32 a93, v165
	v_accvgpr_write_b32 a94, v166
	v_accvgpr_write_b32 a95, v167
	v_accvgpr_write_b32 a77, v169
	v_accvgpr_write_b32 a78, v170
	v_accvgpr_write_b32 a79, v171
	v_accvgpr_write_b32 a65, v173
	v_accvgpr_write_b32 a66, v174
	v_accvgpr_write_b32 a67, v175
	v_accvgpr_write_b32 a41, v193
	v_accvgpr_write_b32 a42, v194
	v_accvgpr_write_b32 a43, v195
	v_accvgpr_write_b32 a29, v197
	v_accvgpr_write_b32 a30, v198
	v_accvgpr_write_b32 a31, v199
	v_accvgpr_write_b32 a9, v201
	v_accvgpr_write_b32 a10, v202
	v_accvgpr_write_b32 a11, v203
	v_accvgpr_write_b32 a1, v205
	v_accvgpr_write_b32 a2, v206
	v_accvgpr_write_b32 a3, v207
.LBB0_2000:
	v_max3_f32 v160, v226, v80, v81
	v_mov_b32_e32 v162, v224
	v_max3_f32 v160, v160, v82, v83
	v_accvgpr_read_b32 v175, a147
	v_max3_f32 v160, v160, v72, v73
	v_lshlrev_b32_e32 v162, 2, v162
	v_max3_f32 v160, v160, v74, v75
	v_bitop3_b32 v162, v162, s23, v227 bitop3:0x6c
	v_max3_f32 v160, v160, v52, v53
	v_accvgpr_read_b32 v171, a151
	v_max3_f32 v160, v160, v54, v55
	v_accvgpr_read_b32 v167, a155
	v_max3_f32 v160, v160, v48, v49
	v_accvgpr_read_b32 v174, a146
	v_max3_f32 v160, v160, v50, v51
	v_mov_b32_e32 v161, v160
	v_mov_b32_e32 v192, v160
	s_nop 1
	v_permlane16_swap_b32_e32 v161, v192
	v_max_f32_e32 v192, v161, v192
	v_mov_b32_e32 v193, v192
	v_mov_b32_e32 v161, v192
	s_nop 1
	v_permlane32_swap_b32_e32 v193, v161
	v_max_f32_e32 v192, v193, v161
	v_add_f32_e32 v193, 0x41000000, v244
	v_mul_f32_e32 v192, 0x3e16c740, v192
	v_accvgpr_read_b32 v163, a159
	v_cmp_gt_f32_e32 vcc, v192, v193
	v_accvgpr_read_b32 v173, a145
	v_accvgpr_read_b32 v172, a144
	v_accvgpr_read_b32 v170, a150
	v_accvgpr_read_b32 v169, a149
	v_accvgpr_read_b32 v168, a148
	v_accvgpr_read_b32 v166, a154
	v_accvgpr_read_b32 v165, a153
	v_accvgpr_read_b32 v164, a152
	v_accvgpr_read_b32 v162, a158
	v_accvgpr_read_b32 v161, a157
	v_accvgpr_read_b32 v160, a156
	v_cndmask_b32_e32 v192, v244, v192, vcc
	s_cbranch_vccz .LBB0_2002
; DI float max3_(float a, float b, float c) { float r; asm("v_max3_f32 %0, %1, %2, %3" : "=v"(r) : "v"(a), "v"(b), "v"(c)); return r; }
; template <int DQK, bool BIAS>
; __device__ __forceinline__ void attn_pass(const hf* __restrict__ Q, int ldq, const hf* __restrict__ Kp, int ldk, const hf* __restrict__ VT,
;                                           int s0, int L, int q0, float scale_l2, const float* sBias, f4 (&oacc)[8][4], char* smem) {
;     ...
;       float mx = -1e30f;
; #pragma unroll
;       for (int mk = 0; mk < 4; ++mk) { mx = max3_(mx, sacc[mk][nq][0], sacc[mk][nq][1]); mx = max3_(mx, sacc[mk][nq][2], sacc[mk][nq][3]); }
;       mx = max3_(mx, shx(mx, 16), mx); mx = max3_(mx, shx(mx, 32), mx);
;       if (!BIAS) mx *= scale_l2;
;       const bool upd = mx > mrun[nq] + 8.f;
;       const float mnew = upd ? mx : mrun[nq];
;       if (__builtin_amdgcn_ballot_w64(upd) != 0) {
;         const float alpha = __builtin_amdgcn_exp2f(mrun[nq] - mnew);
;         lrun[nq] *= alpha;
; #pragma unroll
;         for (int md = 0; md < 8; ++md) { oacc[md][nq][0] *= alpha; oacc[md][nq][1] *= alpha; oacc[md][nq][2] *= alpha; oacc[md][nq][3] *= alpha; }
;       }
	v_sub_f32_e32 v193, v244, v192
	v_exp_f32_e32 v194, v193
	s_nop 0
	v_pk_mul_f32 v[188:189], v[188:189], v[194:195] op_sel_hi:[1,0]
	v_pk_mul_f32 v[184:185], v[184:185], v[194:195] op_sel_hi:[1,0]
	v_pk_mul_f32 v[180:181], v[180:181], v[194:195] op_sel_hi:[1,0]
	v_pk_mul_f32 v[176:177], v[176:177], v[194:195] op_sel_hi:[1,0]
	v_pk_mul_f32 v[124:125], v[124:125], v[194:195] op_sel_hi:[1,0]
	v_pk_mul_f32 v[104:105], v[104:105], v[194:195] op_sel_hi:[1,0]
	v_pk_mul_f32 v[86:87], v[86:87], v[194:195] op_sel_hi:[1,0]
	v_pk_mul_f32 v[78:79], v[78:79], v[194:195] op_sel_hi:[1,0]
	v_pk_mul_f32 v[190:191], v[190:191], v[194:195] op_sel_hi:[1,0]
	v_pk_mul_f32 v[186:187], v[186:187], v[194:195] op_sel_hi:[1,0]
	v_pk_mul_f32 v[182:183], v[182:183], v[194:195] op_sel_hi:[1,0]
	v_pk_mul_f32 v[178:179], v[178:179], v[194:195] op_sel_hi:[1,0]
	v_pk_mul_f32 v[126:127], v[126:127], v[194:195] op_sel_hi:[1,0]
	v_pk_mul_f32 v[106:107], v[106:107], v[194:195] op_sel_hi:[1,0]
	v_pk_mul_f32 v[84:85], v[84:85], v[194:195] op_sel_hi:[1,0]
	v_pk_mul_f32 v[76:77], v[76:77], v[194:195] op_sel_hi:[1,0]
	v_accvgpr_write_b32 a103, v87
	v_accvgpr_write_b32 a119, v79
	v_accvgpr_write_b32 a84, v104
	v_accvgpr_write_b32 a68, v124
	v_accvgpr_write_b32 a48, v176
	v_accvgpr_write_b32 a32, v180
	v_accvgpr_write_b32 a16, v184
	v_accvgpr_write_b32 a4, v188
	v_mul_f32_e32 v237, v237, v194
	v_accvgpr_write_b32 a118, v78
	v_accvgpr_write_b32 a117, v77
	v_accvgpr_write_b32 a116, v76
	v_accvgpr_write_b32 a102, v86
	v_accvgpr_write_b32 a101, v85
	v_accvgpr_write_b32 a100, v84
	v_accvgpr_write_b32 a85, v105
	v_accvgpr_write_b32 a86, v106
	v_accvgpr_write_b32 a87, v107
	v_accvgpr_write_b32 a69, v125
	v_accvgpr_write_b32 a70, v126
	v_accvgpr_write_b32 a71, v127
	v_accvgpr_write_b32 a49, v177
	v_accvgpr_write_b32 a50, v178
	v_accvgpr_write_b32 a51, v179
	v_accvgpr_write_b32 a33, v181
	v_accvgpr_write_b32 a34, v182
	v_accvgpr_write_b32 a35, v183
	v_accvgpr_write_b32 a17, v185
	v_accvgpr_write_b32 a18, v186
	v_accvgpr_write_b32 a19, v187
	v_accvgpr_write_b32 a5, v189
	v_accvgpr_write_b32 a6, v190
	v_accvgpr_write_b32 a7, v191
.LBB0_2002:
	v_max3_f32 v76, v226, v172, v173
	v_mov_b32_e32 v78, v224
	v_max3_f32 v76, v76, v174, v175
	v_accvgpr_read_b32 v124, a128
	v_max3_f32 v76, v76, v168, v169
	v_lshlrev_b32_e32 v78, 2, v78
	v_max3_f32 v76, v76, v170, v171
	v_bitop3_b32 v78, v78, s23, v227 bitop3:0x6c
	v_max3_f32 v76, v76, v164, v165
	v_accvgpr_read_b32 v104, a132
	v_max3_f32 v76, v76, v166, v167
	v_accvgpr_read_b32 v84, a136
	v_max3_f32 v76, v76, v160, v161
	v_accvgpr_read_b32 v125, a129
	v_max3_f32 v76, v76, v162, v163
	v_mov_b32_e32 v77, v76
	v_mov_b32_e32 v176, v76
	s_nop 1
	v_permlane16_swap_b32_e32 v77, v176
	v_max_f32_e32 v176, v77, v176
	v_mov_b32_e32 v177, v176
	v_mov_b32_e32 v77, v176
	s_nop 1
	v_permlane32_swap_b32_e32 v177, v77
	v_max_f32_e32 v176, v177, v77
	v_add_f32_e32 v177, 0x41000000, v243
	v_mul_f32_e32 v176, 0x3e16c740, v176
	v_accvgpr_read_b32 v76, a140
	v_cmp_gt_f32_e32 vcc, v176, v177
	v_accvgpr_read_b32 v126, a130
	v_accvgpr_read_b32 v127, a131
	v_accvgpr_read_b32 v105, a133
	v_accvgpr_read_b32 v106, a134
	v_accvgpr_read_b32 v107, a135
	v_accvgpr_read_b32 v85, a137
	v_accvgpr_read_b32 v86, a138
	v_accvgpr_read_b32 v87, a139
	v_accvgpr_read_b32 v77, a141
	v_accvgpr_read_b32 v78, a142
	v_accvgpr_read_b32 v79, a143
	v_cndmask_b32_e32 v176, v243, v176, vcc
	s_cbranch_vccz .LBB0_2004
	v_sub_f32_e32 v177, v243, v176
	v_exp_f32_e32 v178, v177
	s_nop 0
	v_pk_mul_f32 v[156:157], v[156:157], v[178:179] op_sel_hi:[1,0]
	v_pk_mul_f32 v[152:153], v[152:153], v[178:179] op_sel_hi:[1,0]
	v_pk_mul_f32 v[148:149], v[148:149], v[178:179] op_sel_hi:[1,0]
	v_pk_mul_f32 v[144:145], v[144:145], v[178:179] op_sel_hi:[1,0]
	v_pk_mul_f32 v[140:141], v[140:141], v[178:179] op_sel_hi:[1,0]
	v_pk_mul_f32 v[136:137], v[136:137], v[178:179] op_sel_hi:[1,0]
	v_pk_mul_f32 v[132:133], v[132:133], v[178:179] op_sel_hi:[1,0]
	v_pk_mul_f32 v[128:129], v[128:129], v[178:179] op_sel_hi:[1,0]
	v_pk_mul_f32 v[158:159], v[158:159], v[178:179] op_sel_hi:[1,0]
	v_pk_mul_f32 v[154:155], v[154:155], v[178:179] op_sel_hi:[1,0]
	v_pk_mul_f32 v[150:151], v[150:151], v[178:179] op_sel_hi:[1,0]
	v_pk_mul_f32 v[146:147], v[146:147], v[178:179] op_sel_hi:[1,0]
	v_pk_mul_f32 v[142:143], v[142:143], v[178:179] op_sel_hi:[1,0]
	v_pk_mul_f32 v[138:139], v[138:139], v[178:179] op_sel_hi:[1,0]
	v_pk_mul_f32 v[134:135], v[134:135], v[178:179] op_sel_hi:[1,0]
	v_pk_mul_f32 v[130:131], v[130:131], v[178:179] op_sel_hi:[1,0]
	v_accvgpr_write_b32 a104, v132
	v_accvgpr_write_b32 a120, v128
	v_accvgpr_write_b32 a88, v136
	v_accvgpr_write_b32 a72, v140
	v_accvgpr_write_b32 a56, v144
	v_accvgpr_write_b32 a44, v148
	v_accvgpr_write_b32 a24, v152
	v_accvgpr_write_b32 a12, v156
	v_mul_f32_e32 v236, v236, v178
	v_accvgpr_write_b32 a121, v129
	v_accvgpr_write_b32 a122, v130
	v_accvgpr_write_b32 a123, v131
	v_accvgpr_write_b32 a105, v133
	v_accvgpr_write_b32 a106, v134
	v_accvgpr_write_b32 a107, v135
	v_accvgpr_write_b32 a89, v137
	v_accvgpr_write_b32 a90, v138
	v_accvgpr_write_b32 a91, v139
	v_accvgpr_write_b32 a73, v141
	v_accvgpr_write_b32 a74, v142
	v_accvgpr_write_b32 a75, v143
	v_accvgpr_write_b32 a57, v145
	v_accvgpr_write_b32 a58, v146
	v_accvgpr_write_b32 a59, v147
	v_accvgpr_write_b32 a45, v149
	v_accvgpr_write_b32 a46, v150
	v_accvgpr_write_b32 a47, v151
	v_accvgpr_write_b32 a25, v153
	v_accvgpr_write_b32 a26, v154
	v_accvgpr_write_b32 a27, v155
	v_accvgpr_write_b32 a13, v157
	v_accvgpr_write_b32 a14, v158
	v_accvgpr_write_b32 a15, v159
; DI float max3_(float a, float b, float c) { float r; asm("v_max3_f32 %0, %1, %2, %3" : "=v"(r) : "v"(a), "v"(b), "v"(c)); return r; }
; template <int DQK, bool BIAS>
; __device__ __forceinline__ void attn_pass(const hf* __restrict__ Q, int ldq, const hf* __restrict__ Kp, int ldk, const hf* __restrict__ VT,
;                                           int s0, int L, int q0, float scale_l2, const float* sBias, f4 (&oacc)[8][4], char* smem) {
;     ...
;       float mx = -1e30f;
; #pragma unroll
;       for (int mk = 0; mk < 4; ++mk) { mx = max3_(mx, sacc[mk][nq][0], sacc[mk][nq][1]); mx = max3_(mx, sacc[mk][nq][2], sacc[mk][nq][3]); }
;       mx = max3_(mx, shx(mx, 16), mx); mx = max3_(mx, shx(mx, 32), mx);
;       if (!BIAS) mx *= scale_l2;
;       const bool upd = mx > mrun[nq] + 8.f;
;       const float mnew = upd ? mx : mrun[nq];
;       if (__builtin_amdgcn_ballot_w64(upd) != 0) {
;         const float alpha = __builtin_amdgcn_exp2f(mrun[nq] - mnew);
;         lrun[nq] *= alpha;
; #pragma unroll
;         for (int md = 0; md < 8; ++md) { oacc[md][nq][0] *= alpha; oacc[md][nq][1] *= alpha; oacc[md][nq][2] *= alpha; oacc[md][nq][3] *= alpha; }
;       }
.LBB0_2004:
	v_max3_f32 v128, v226, v124, v125
	v_mov_b32_e32 v130, v224
	v_max3_f32 v128, v128, v126, v127
	s_nop 0
	v_max3_f32 v128, v128, v104, v105
	v_lshlrev_b32_e32 v130, 2, v130
	v_max3_f32 v128, v128, v106, v107
	v_bitop3_b32 v130, v130, s23, v227 bitop3:0x6c
	v_max3_f32 v128, v128, v84, v85
	s_nop 0
	v_max3_f32 v128, v128, v86, v87
	s_nop 0
	v_max3_f32 v128, v128, v76, v77
	s_nop 0
	v_max3_f32 v128, v128, v78, v79
	v_mov_b32_e32 v129, v128
	s_nop 1
	v_permlane16_swap_b32_e32 v129, v128
	v_max_f32_e32 v128, v128, v129
	v_mov_b32_e32 v129, v128
	s_nop 1
	v_permlane32_swap_b32_e32 v129, v128
	v_max_f32_e32 v128, v128, v129
	v_add_f32_e32 v130, 0x41000000, v242
	v_mul_f32_e32 v128, 0x3e16c740, v128
	v_cmp_gt_f32_e32 vcc, v128, v130
	s_nop 1
	v_cndmask_b32_e32 v128, v242, v128, vcc
	s_cbranch_vccz .LBB0_2006
	v_sub_f32_e32 v129, v242, v128
	v_exp_f32_e32 v130, v129
	s_nop 0
	v_pk_mul_f32 v[120:121], v[120:121], v[130:131] op_sel_hi:[1,0]
	v_pk_mul_f32 v[116:117], v[116:117], v[130:131] op_sel_hi:[1,0]
	v_pk_mul_f32 v[112:113], v[112:113], v[130:131] op_sel_hi:[1,0]
	v_pk_mul_f32 v[108:109], v[108:109], v[130:131] op_sel_hi:[1,0]
	v_pk_mul_f32 v[100:101], v[100:101], v[130:131] op_sel_hi:[1,0]
	v_pk_mul_f32 v[96:97], v[96:97], v[130:131] op_sel_hi:[1,0]
	v_pk_mul_f32 v[94:95], v[94:95], v[130:131] op_sel_hi:[1,0]
	v_pk_mul_f32 v[90:91], v[90:91], v[130:131] op_sel_hi:[1,0]
	v_pk_mul_f32 v[122:123], v[122:123], v[130:131] op_sel_hi:[1,0]
	v_pk_mul_f32 v[118:119], v[118:119], v[130:131] op_sel_hi:[1,0]
	v_pk_mul_f32 v[114:115], v[114:115], v[130:131] op_sel_hi:[1,0]
	v_pk_mul_f32 v[110:111], v[110:111], v[130:131] op_sel_hi:[1,0]
	v_pk_mul_f32 v[102:103], v[102:103], v[130:131] op_sel_hi:[1,0]
	v_pk_mul_f32 v[98:99], v[98:99], v[130:131] op_sel_hi:[1,0]
	v_pk_mul_f32 v[92:93], v[92:93], v[130:131] op_sel_hi:[1,0]
	v_pk_mul_f32 v[88:89], v[88:89], v[130:131] op_sel_hi:[1,0]
	v_accvgpr_write_b32 a115, v95
	v_accvgpr_write_b32 a127, v91
	v_accvgpr_write_b32 a96, v96
	v_accvgpr_write_b32 a80, v100
	v_accvgpr_write_b32 a60, v108
	v_accvgpr_write_b32 a52, v112
	v_accvgpr_write_b32 a36, v116
	v_accvgpr_write_b32 a20, v120
	v_mul_f32_e32 v235, v235, v130
	v_accvgpr_write_b32 a126, v90
	v_accvgpr_write_b32 a125, v89
	v_accvgpr_write_b32 a124, v88
	v_accvgpr_write_b32 a114, v94
	v_accvgpr_write_b32 a113, v93
	v_accvgpr_write_b32 a112, v92
	v_accvgpr_write_b32 a97, v97
	v_accvgpr_write_b32 a98, v98
	v_accvgpr_write_b32 a99, v99
	v_accvgpr_write_b32 a81, v101
	v_accvgpr_write_b32 a82, v102
	v_accvgpr_write_b32 a83, v103
	v_accvgpr_write_b32 a61, v109
	v_accvgpr_write_b32 a62, v110
	v_accvgpr_write_b32 a63, v111
	v_accvgpr_write_b32 a53, v113
	v_accvgpr_write_b32 a54, v114
	v_accvgpr_write_b32 a55, v115
	v_accvgpr_write_b32 a37, v117
	v_accvgpr_write_b32 a38, v118
	v_accvgpr_write_b32 a39, v119
	v_accvgpr_write_b32 a21, v121
	v_accvgpr_write_b32 a22, v122
	v_accvgpr_write_b32 a23, v123
